# 7.3 widened epilogue stores (permlane32_swap -> dwordx4) in P5 and P7 GEMM epilogues
# speedup vs baseline: 1.0142x; 1.0051x over previous
; DI unsigned pk2(float a, float b) { f2_t v = {a, b}; bf2_t r = __builtin_convertvector(v, bf2_t); return __builtin_bit_cast(unsigned, r); }
; DI void phase5(const Params& p, char* smem) {
;     ...
;     gemm_tile<true>(MG, D_, W, D_, D_, tm * 128, tn * 128, smem, [&](f32x16 (&acc)[2][2], int mb, int nb, int r, int hi) __attribute__((always_inline)) {
; #pragma unroll
;       for (int mi = 0; mi < 2; ++mi) {
;         const int row = mb + mi * 32 + r, b = row >> 11;
;         const float* gt = mod + b * 12288 + 2 * 2048;
; #pragma unroll
;         for (int ni = 0; ni < 2; ++ni)
; #pragma unroll
;           for (int g = 0; g < 4; ++g) {
;             const int col = nb + ni * 32 + hi * 4 + 8 * g;
;             const float4 xv = *(const float4*)(X + (size_t)row * D_ + col), gv = *(const float4*)(gt + col);
;             float4 o;
;             o.x = xv.x + gv.x * acc[mi][ni][4 * g]; o.y = xv.y + gv.y * acc[mi][ni][4 * g + 1]; o.z = xv.z + gv.z * acc[mi][ni][4 * g + 2]; o.w = xv.w + gv.w * acc[mi][ni][4 * g + 3];
;             *(uint2*)(X1 + (size_t)row * D_ + col) = make_uint2(pk2(o.x, o.y), pk2(o.z, o.w));
;           }
;       }
;     });
.LBB0_745:
	v_add_u32_e32 v190, s18, v146
	v_ashrrev_i32_e32 v192, 11, v190
	v_mul_i32_i24_e32 v192, 0x3000, v192
	v_ashrrev_i32_e32 v193, 31, v192
	v_or_b32_e32 v194, s19, v149
	v_lshl_add_u64 v[192:193], v[192:193], 2, s[82:83]
	v_ashrrev_i32_e32 v191, 31, v190
	v_lshl_add_u64 v[196:197], v[192:193], 0, s[6:7]
	v_lshlrev_b64 v[192:193], 13, v[190:191]
	v_ashrrev_i32_e32 v195, 31, v194
	v_lshl_add_u64 v[192:193], s[56:57], 0, v[192:193]
	v_lshlrev_b64 v[198:199], 2, v[194:195]
	v_lshl_add_u64 v[200:201], v[192:193], 0, v[198:199]
	v_lshl_add_u64 v[202:203], v[196:197], 0, v[198:199]
	global_load_dwordx4 v[150:153], v[202:203], off
	global_load_dwordx4 v[154:157], v[202:203], off offset:32
	global_load_dwordx4 v[158:161], v[202:203], off offset:64
	global_load_dwordx4 v[162:165], v[202:203], off offset:96
	global_load_dwordx4 v[166:169], v[202:203], off offset:128
	global_load_dwordx4 v[170:173], v[202:203], off offset:160
	global_load_dwordx4 v[174:177], v[202:203], off offset:192
	global_load_dwordx4 v[178:181], v[202:203], off offset:224
	global_load_dwordx4 v[66:69], v[200:201], off
	global_load_dwordx4 v[70:73], v[200:201], off offset:32
	global_load_dwordx4 v[74:77], v[200:201], off offset:64
	global_load_dwordx4 v[78:81], v[200:201], off offset:96
	global_load_dwordx4 v[82:85], v[200:201], off offset:128
	global_load_dwordx4 v[86:89], v[200:201], off offset:160
	global_load_dwordx4 v[90:93], v[200:201], off offset:192
	global_load_dwordx4 v[94:97], v[200:201], off offset:224
	v_or_b32_e32 v212, 32, v190
	v_ashrrev_i32_e32 v213, 31, v212
	v_lshlrev_b64 v[208:209], 13, v[212:213]
	v_lshl_add_u64 v[208:209], s[56:57], 0, v[208:209]
	v_lshl_add_u64 v[208:209], v[208:209], 0, v[198:199]
	global_load_dwordx4 v[98:101], v[208:209], off
	global_load_dwordx4 v[102:105], v[208:209], off offset:32
	global_load_dwordx4 v[106:109], v[208:209], off offset:64
	global_load_dwordx4 v[110:113], v[208:209], off offset:96
	global_load_dwordx4 v[114:117], v[208:209], off offset:128
	global_load_dwordx4 v[118:121], v[208:209], off offset:160
	global_load_dwordx4 v[122:125], v[208:209], off offset:192
	global_load_dwordx4 v[126:129], v[208:209], off offset:224
	v_lshlrev_b64 v[204:205], 12, v[190:191]
	v_lshlrev_b64 v[206:207], 1, v[194:195]
	v_and_b32_e32 v214, 32, v0
	v_lshrrev_b32_e32 v214, 2, v214
	v_mov_b32_e32 v215, 0
	v_lshl_add_u64 v[206:207], v[206:207], 0, v[214:215]
	v_lshl_add_u64 v[204:205], s[2:3], 0, v[204:205]
	v_lshl_add_u64 v[204:205], v[204:205], 0, v[206:207]
	v_lshlrev_b64 v[210:211], 12, v[212:213]
	v_lshl_add_u64 v[210:211], s[2:3], 0, v[210:211]
	v_lshl_add_u64 v[210:211], v[210:211], 0, v[206:207]
	s_add_i32 s17, s17, s13
	s_cmpk_lt_i32 s17, 0x400
	s_waitcnt vmcnt(15)
	v_pk_fma_f32 v[50:51], v[50:51], v[150:151], v[66:67]
	v_pk_fma_f32 v[52:53], v[52:53], v[152:153], v[68:69]
	v_cvt_pk_bf16_f32 v50, v50, v51
	v_cvt_pk_bf16_f32 v51, v52, v53
	s_waitcnt vmcnt(14)
	v_pk_fma_f32 v[54:55], v[54:55], v[154:155], v[70:71]
	v_pk_fma_f32 v[56:57], v[56:57], v[156:157], v[72:73]
	v_cvt_pk_bf16_f32 v52, v54, v55
	v_cvt_pk_bf16_f32 v53, v56, v57
	s_nop 1
	v_permlane32_swap_b32_e32 v50, v52
	v_permlane32_swap_b32_e32 v51, v53
	global_store_dwordx4 v[204:205], v[50:53], off
	s_waitcnt vmcnt(14)
	v_pk_fma_f32 v[58:59], v[58:59], v[158:159], v[74:75]
	v_pk_fma_f32 v[60:61], v[60:61], v[160:161], v[76:77]
	v_cvt_pk_bf16_f32 v58, v58, v59
	v_cvt_pk_bf16_f32 v59, v60, v61
	s_waitcnt vmcnt(13)
	v_pk_fma_f32 v[62:63], v[62:63], v[162:163], v[78:79]
	v_pk_fma_f32 v[64:65], v[64:65], v[164:165], v[80:81]
	v_cvt_pk_bf16_f32 v60, v62, v63
	v_cvt_pk_bf16_f32 v61, v64, v65
	s_nop 1
	v_permlane32_swap_b32_e32 v58, v60
	v_permlane32_swap_b32_e32 v59, v61
	global_store_dwordx4 v[204:205], v[58:61], off offset:32
	s_waitcnt vmcnt(13)
	v_pk_fma_f32 v[34:35], v[34:35], v[166:167], v[82:83]
	v_pk_fma_f32 v[36:37], v[36:37], v[168:169], v[84:85]
	v_cvt_pk_bf16_f32 v34, v34, v35
	v_cvt_pk_bf16_f32 v35, v36, v37
	s_waitcnt vmcnt(12)
	v_pk_fma_f32 v[38:39], v[38:39], v[170:171], v[86:87]
	v_pk_fma_f32 v[40:41], v[40:41], v[172:173], v[88:89]
	v_cvt_pk_bf16_f32 v36, v38, v39
	v_cvt_pk_bf16_f32 v37, v40, v41
	s_nop 1
	v_permlane32_swap_b32_e32 v34, v36
	v_permlane32_swap_b32_e32 v35, v37
	global_store_dwordx4 v[204:205], v[34:37], off offset:64
	s_waitcnt vmcnt(12)
	v_pk_fma_f32 v[42:43], v[42:43], v[174:175], v[90:91]
	v_pk_fma_f32 v[44:45], v[44:45], v[176:177], v[92:93]
	v_cvt_pk_bf16_f32 v42, v42, v43
	v_cvt_pk_bf16_f32 v43, v44, v45
	s_waitcnt vmcnt(11)
	v_pk_fma_f32 v[46:47], v[46:47], v[178:179], v[94:95]
	v_pk_fma_f32 v[48:49], v[48:49], v[180:181], v[96:97]
	v_cvt_pk_bf16_f32 v44, v46, v47
	v_cvt_pk_bf16_f32 v45, v48, v49
	s_nop 1
	v_permlane32_swap_b32_e32 v42, v44
	v_permlane32_swap_b32_e32 v43, v45
	global_store_dwordx4 v[204:205], v[42:45], off offset:96
	s_waitcnt vmcnt(11)
	v_pk_fma_f32 v[18:19], v[18:19], v[150:151], v[98:99]
	v_pk_fma_f32 v[20:21], v[20:21], v[152:153], v[100:101]
	v_cvt_pk_bf16_f32 v18, v18, v19
	v_cvt_pk_bf16_f32 v19, v20, v21
	s_waitcnt vmcnt(10)
	v_pk_fma_f32 v[22:23], v[22:23], v[154:155], v[102:103]
	v_pk_fma_f32 v[24:25], v[24:25], v[156:157], v[104:105]
	v_cvt_pk_bf16_f32 v20, v22, v23
	v_cvt_pk_bf16_f32 v21, v24, v25
	s_nop 1
	v_permlane32_swap_b32_e32 v18, v20
	v_permlane32_swap_b32_e32 v19, v21
	global_store_dwordx4 v[210:211], v[18:21], off
	s_waitcnt vmcnt(10)
	v_pk_fma_f32 v[26:27], v[26:27], v[158:159], v[106:107]
	v_pk_fma_f32 v[28:29], v[28:29], v[160:161], v[108:109]
	v_cvt_pk_bf16_f32 v26, v26, v27
	v_cvt_pk_bf16_f32 v27, v28, v29
	s_waitcnt vmcnt(9)
	v_pk_fma_f32 v[30:31], v[30:31], v[162:163], v[110:111]
	v_pk_fma_f32 v[32:33], v[32:33], v[164:165], v[112:113]
	v_cvt_pk_bf16_f32 v28, v30, v31
	v_cvt_pk_bf16_f32 v29, v32, v33
	s_nop 1
	v_permlane32_swap_b32_e32 v26, v28
	v_permlane32_swap_b32_e32 v27, v29
	global_store_dwordx4 v[210:211], v[26:29], off offset:32
	s_waitcnt vmcnt(9)
	v_pk_fma_f32 v[2:3], v[2:3], v[166:167], v[114:115]
	v_pk_fma_f32 v[4:5], v[4:5], v[168:169], v[116:117]
	v_cvt_pk_bf16_f32 v2, v2, v3
	v_cvt_pk_bf16_f32 v3, v4, v5
	s_waitcnt vmcnt(8)
	v_pk_fma_f32 v[6:7], v[6:7], v[170:171], v[118:119]
	v_pk_fma_f32 v[8:9], v[8:9], v[172:173], v[120:121]
	v_cvt_pk_bf16_f32 v4, v6, v7
	v_cvt_pk_bf16_f32 v5, v8, v9
	s_nop 1
	v_permlane32_swap_b32_e32 v2, v4
	v_permlane32_swap_b32_e32 v3, v5
	global_store_dwordx4 v[210:211], v[2:5], off offset:64
	s_waitcnt vmcnt(8)
	v_pk_fma_f32 v[10:11], v[10:11], v[174:175], v[122:123]
	v_pk_fma_f32 v[12:13], v[12:13], v[176:177], v[124:125]
	v_cvt_pk_bf16_f32 v10, v10, v11
	v_cvt_pk_bf16_f32 v11, v12, v13
	s_waitcnt vmcnt(7)
	v_pk_fma_f32 v[14:15], v[14:15], v[178:179], v[126:127]
	v_pk_fma_f32 v[16:17], v[16:17], v[180:181], v[128:129]
	v_cvt_pk_bf16_f32 v12, v14, v15
	v_cvt_pk_bf16_f32 v13, v16, v17
	s_nop 1
	v_permlane32_swap_b32_e32 v10, v12
	v_permlane32_swap_b32_e32 v11, v13
	global_store_dwordx4 v[210:211], v[10:13], off offset:96
	s_cbranch_scc0 .LBB0_754

; DI unsigned pk2(float a, float b) { f2_t v = {a, b}; bf2_t r = __builtin_convertvector(v, bf2_t); return __builtin_bit_cast(unsigned, r); }
; DI void phase7(const Params& p, char* smem) {
;     ...
;     gemm_tile<true>(H2, D_, W, D_, D_, tm * 128, tn * 128, smem, [&](f32x16 (&acc)[2][2], int mb, int nb, int r, int hi) __attribute__((always_inline)) {
; #pragma unroll
;       for (int mi = 0; mi < 2; ++mi)
; #pragma unroll
;         for (int ni = 0; ni < 2; ++ni)
; #pragma unroll
;           for (int g = 0; g < 4; ++g) {
;             const int row = mb + mi * 32 + r, col = nb + ni * 32 + hi * 4 + 8 * g;
;             *(uint2*)(PQ + (size_t)row * D_ + col) = make_uint2(pk2(acc[mi][ni][4 * g], acc[mi][ni][4 * g + 1]), pk2(acc[mi][ni][4 * g + 2], acc[mi][ni][4 * g + 3]));
;           }
;     });
.LBB0_952:
	v_add_u32_e32 v66, s16, v146
	v_or_b32_e32 v68, s17, v149
	v_ashrrev_i32_e32 v67, 31, v66
	v_lshlrev_b64 v[70:71], 12, v[66:67]
	v_ashrrev_i32_e32 v69, 31, v68
	v_lshl_add_u64 v[72:73], s[2:3], 0, v[70:71]
	v_lshlrev_b64 v[68:69], 1, v[68:69]
	v_and_b32_e32 v74, 32, v0
	v_lshrrev_b32_e32 v74, 2, v74
	v_mov_b32_e32 v75, 0
	v_lshl_add_u64 v[68:69], v[68:69], 0, v[74:75]
	v_lshl_add_u64 v[72:73], v[72:73], 0, v[68:69]
	v_or_b32_e32 v76, 32, v66
	v_ashrrev_i32_e32 v77, 31, v76
	v_lshlrev_b64 v[76:77], 12, v[76:77]
	v_lshl_add_u64 v[76:77], s[2:3], 0, v[76:77]
	v_lshl_add_u64 v[76:77], v[76:77], 0, v[68:69]
	s_add_i32 s15, s15, s10
	s_cmpk_lt_i32 s15, 0x400
	v_cvt_pk_bf16_f32 v50, v50, v51
	v_cvt_pk_bf16_f32 v51, v52, v53
	v_cvt_pk_bf16_f32 v52, v54, v55
	v_cvt_pk_bf16_f32 v53, v56, v57
	v_cvt_pk_bf16_f32 v54, v58, v59
	v_cvt_pk_bf16_f32 v55, v60, v61
	v_cvt_pk_bf16_f32 v56, v62, v63
	v_cvt_pk_bf16_f32 v57, v64, v65
	v_permlane32_swap_b32_e32 v50, v52
	v_permlane32_swap_b32_e32 v51, v53
	v_permlane32_swap_b32_e32 v54, v56
	v_permlane32_swap_b32_e32 v55, v57
	global_store_dwordx4 v[72:73], v[50:53], off
	global_store_dwordx4 v[72:73], v[54:57], off offset:32
	v_cvt_pk_bf16_f32 v34, v34, v35
	v_cvt_pk_bf16_f32 v35, v36, v37
	v_cvt_pk_bf16_f32 v36, v38, v39
	v_cvt_pk_bf16_f32 v37, v40, v41
	v_cvt_pk_bf16_f32 v38, v42, v43
	v_cvt_pk_bf16_f32 v39, v44, v45
	v_cvt_pk_bf16_f32 v40, v46, v47
	v_cvt_pk_bf16_f32 v41, v48, v49
	v_permlane32_swap_b32_e32 v34, v36
	v_permlane32_swap_b32_e32 v35, v37
	v_permlane32_swap_b32_e32 v38, v40
	v_permlane32_swap_b32_e32 v39, v41
	global_store_dwordx4 v[72:73], v[34:37], off offset:64
	global_store_dwordx4 v[72:73], v[38:41], off offset:96
	v_cvt_pk_bf16_f32 v18, v18, v19
	v_cvt_pk_bf16_f32 v19, v20, v21
	v_cvt_pk_bf16_f32 v20, v22, v23
	v_cvt_pk_bf16_f32 v21, v24, v25
	v_cvt_pk_bf16_f32 v22, v26, v27
	v_cvt_pk_bf16_f32 v23, v28, v29
	v_cvt_pk_bf16_f32 v24, v30, v31
	v_cvt_pk_bf16_f32 v25, v32, v33
	v_permlane32_swap_b32_e32 v18, v20
	v_permlane32_swap_b32_e32 v19, v21
	v_permlane32_swap_b32_e32 v22, v24
	v_permlane32_swap_b32_e32 v23, v25
	global_store_dwordx4 v[76:77], v[18:21], off
	global_store_dwordx4 v[76:77], v[22:25], off offset:32
	v_cvt_pk_bf16_f32 v2, v2, v3
	v_cvt_pk_bf16_f32 v3, v4, v5
	v_cvt_pk_bf16_f32 v4, v6, v7
	v_cvt_pk_bf16_f32 v5, v8, v9
	v_cvt_pk_bf16_f32 v6, v10, v11
	v_cvt_pk_bf16_f32 v7, v12, v13
	v_cvt_pk_bf16_f32 v8, v14, v15
	v_cvt_pk_bf16_f32 v9, v16, v17
	v_permlane32_swap_b32_e32 v2, v4
	v_permlane32_swap_b32_e32 v3, v5
	v_permlane32_swap_b32_e32 v6, v8
	v_permlane32_swap_b32_e32 v7, v9
	global_store_dwordx4 v[76:77], v[2:5], off offset:64
	global_store_dwordx4 v[76:77], v[6:9], off offset:96
	s_cbranch_scc0 .LBB0_961
